# speedup vs baseline: 1.0117x; 1.0117x over previous
; __device__ __forceinline__ void attn_item(KP P, int l, bool isS, int b, int c, int hp, char* smem) {
;     ...
;     f32x4 s[4];
; #pragma unroll
;     for (int kb = 0; kb < 4; ++kb) {
;       s[kb] = (f32x4){0.f, 0.f, 0.f, 0.f};
; #pragma unroll
;       for (int ks = 0; ks < 4; ++ks) {
;         const bf16x8 kf = *(const bf16x8*)(Ks + (kb * 16 + fr) * 136 + ks * 32 + fq * 8);
;         s[kb] = __builtin_amdgcn_mfma_f32_16x16x32_bf16(kf, qf[ks], s[kb], 0, 0, 0);
;       }
;     }
;     const int qi = wq * 16 + fr;
;     float mx = -1e30f;
; #pragma unroll
;     for (int kb = 0; kb < 4; ++kb) {
; #pragma unroll
;       for (int j = 0; j < 4; ++j) {
;         const int jb = t * 64 + kb * 16 + fq * 4 + j;
;         const bool valid = (!isS) || (jb < 528);
;         int rel = qi + 512 - jb; rel = rel < -128 ? -128 : (rel > 128 ? 128 : rel);
;         const float v = valid ? s[kb][j] * scl + Bi[rel + 128] : -1e30f;
;         s[kb][j] = v;
;         mx = fmaxf(mx, v);
;       }
;     }
.LBB0_478:
	v_add_u32_e32 v119, s0, v114
	s_add_i32 s1, s1, 1
	s_sub_i32 s0, s0, 64
	ds_read_b128 v[128:131], v115
	ds_read_b128 v[132:135], v115 offset:4352
	ds_read_b128 v[136:139], v115 offset:8704
	ds_read_b128 v[140:143], v115 offset:13056
	ds_read_b128 v[144:147], v115 offset:64
	ds_read_b128 v[148:151], v115 offset:4416
	ds_read_b128 v[152:155], v115 offset:8768
	ds_read_b128 v[156:159], v115 offset:13120
	ds_read_b128 v[160:163], v115 offset:128
	ds_read_b128 v[164:167], v115 offset:4480
	ds_read_b128 v[168:171], v115 offset:8832
	ds_read_b128 v[172:175], v115 offset:13184
	ds_read_b128 v[176:179], v115 offset:192
	ds_read_b128 v[180:183], v115 offset:4544
	ds_read_b128 v[184:187], v115 offset:8896
	ds_read_b128 v[192:195], v115 offset:13248
	v_lshl_add_u64 v[104:105], v[104:105], 0, s[52:53]
	s_cmp_lt_u32 s1, 6
	s_cbranch_scc1 .Lfb_fastbias
	v_add_u32_e32 v212, 0x200, v119
	v_add_u32_e32 v213, 0x1ff, v119
	v_add_u32_e32 v214, 0x1fe, v119
	v_add_u32_e32 v215, 0x1fd, v119
	v_add_u32_e32 v216, 0x1f0, v119
	v_add_u32_e32 v217, 0x1ef, v119
	v_add_u32_e32 v218, 0x1ee, v119
	v_add_u32_e32 v219, 0x1ed, v119
	v_min_i32_e32 v212, 0x80, v212
	v_min_i32_e32 v213, 0x80, v213
	v_min_i32_e32 v214, 0x80, v214
	v_min_i32_e32 v215, 0x80, v215
	v_min_i32_e32 v216, 0x80, v216
	v_min_i32_e32 v217, 0x80, v217
	v_min_i32_e32 v218, 0x80, v218
	v_min_i32_e32 v219, 0x80, v219
	v_lshl_add_u32 v212, v212, 2, v110
	v_lshl_add_u32 v213, v213, 2, v110
	v_lshl_add_u32 v214, v214, 2, v110
	v_lshl_add_u32 v215, v215, 2, v110
	v_lshl_add_u32 v216, v216, 2, v110
	v_lshl_add_u32 v217, v217, 2, v110
	v_lshl_add_u32 v218, v218, 2, v110
	v_lshl_add_u32 v219, v219, 2, v110
	ds_read_b32 v124, v212 offset:44544
	ds_read_b32 v120, v213 offset:44544
	ds_read_b32 v125, v214 offset:44544
	ds_read_b32 v122, v215 offset:44544
	ds_read_b32 v123, v216 offset:44544
	ds_read_b32 v126, v217 offset:44544
	ds_read_b32 v97, v218 offset:44544
	ds_read_b32 v98, v219 offset:44544
	v_add_u32_e32 v212, 0x1e0, v119
	v_add_u32_e32 v213, 0x1df, v119
	v_add_u32_e32 v214, 0x1de, v119
	v_add_u32_e32 v215, 0x1dd, v119
	v_add_u32_e32 v216, 0x1d0, v119
	v_add_u32_e32 v217, 0x1cf, v119
	v_add_u32_e32 v218, 0x1ce, v119
	v_add_u32_e32 v219, 0x1cd, v119
	v_min_i32_e32 v212, 0x80, v212
	v_min_i32_e32 v213, 0x80, v213
	v_min_i32_e32 v214, 0x80, v214
	v_min_i32_e32 v215, 0x80, v215
	v_min_i32_e32 v216, 0x80, v216
	v_min_i32_e32 v217, 0x80, v217
	v_min_i32_e32 v218, 0x80, v218
	v_min_i32_e32 v219, 0x80, v219
	v_lshl_add_u32 v212, v212, 2, v110
	v_lshl_add_u32 v213, v213, 2, v110
	v_lshl_add_u32 v214, v214, 2, v110
	v_lshl_add_u32 v215, v215, 2, v110
	v_lshl_add_u32 v216, v216, 2, v110
	v_lshl_add_u32 v217, v217, 2, v110
	v_lshl_add_u32 v218, v218, 2, v110
	v_lshl_add_u32 v219, v219, 2, v110
	ds_read_b32 v99, v212 offset:44544
	ds_read_b32 v92, v213 offset:44544
	ds_read_b32 v121, v214 offset:44544
	ds_read_b32 v94, v215 offset:44544
	ds_read_b32 v95, v216 offset:44544
	ds_read_b32 v127, v217 offset:44544
	ds_read_b32 v93, v218 offset:44544
	ds_read_b32 v119, v219 offset:44544
	s_waitcnt lgkmcnt(15)
	s_branch .Lfb_smfma
.Lfb_fastbias:
	v_mov_b32_e32 v221, 0x3db504f3
	ds_read_b32 v220, v110 offset:45056
	s_waitcnt lgkmcnt(1)
.Lfb_smfma:
	v_mfma_f32_16x16x32_bf16 v[196:199], v[128:131], v[16:19], 0
	v_mfma_f32_16x16x32_bf16 v[200:203], v[132:135], v[16:19], 0
	v_mfma_f32_16x16x32_bf16 v[204:207], v[136:139], v[16:19], 0
	v_mfma_f32_16x16x32_bf16 v[208:211], v[140:143], v[16:19], 0
	v_mfma_f32_16x16x32_bf16 v[196:199], v[144:147], v[8:11], v[196:199]
	v_mfma_f32_16x16x32_bf16 v[200:203], v[148:151], v[8:11], v[200:203]
	v_mfma_f32_16x16x32_bf16 v[204:207], v[152:155], v[8:11], v[204:207]
	v_mfma_f32_16x16x32_bf16 v[208:211], v[156:159], v[8:11], v[208:211]
	v_mfma_f32_16x16x32_bf16 v[196:199], v[160:163], v[12:15], v[196:199]
	v_mfma_f32_16x16x32_bf16 v[200:203], v[164:167], v[12:15], v[200:203]
	v_mfma_f32_16x16x32_bf16 v[204:207], v[168:171], v[12:15], v[204:207]
	v_mfma_f32_16x16x32_bf16 v[208:211], v[172:175], v[12:15], v[208:211]
	v_mfma_f32_16x16x32_bf16 v[196:199], v[176:179], v[20:23], v[196:199]
	v_mfma_f32_16x16x32_bf16 v[200:203], v[180:183], v[20:23], v[200:203]
	v_mfma_f32_16x16x32_bf16 v[204:207], v[184:187], v[20:23], v[204:207]
	v_mfma_f32_16x16x32_bf16 v[208:211], v[192:195], v[20:23], v[208:211]
	ds_read_b64_tr_b16 v[128:129], v116 offset:17408
	ds_read_b64_tr_b16 v[130:131], v116 offset:21760
	ds_read_b64_tr_b16 v[132:133], v116 offset:26112
	ds_read_b64_tr_b16 v[134:135], v116 offset:30464
	ds_read_b64_tr_b16 v[136:137], v116 offset:17440
	ds_read_b64_tr_b16 v[138:139], v116 offset:21792
	ds_read_b64_tr_b16 v[140:141], v116 offset:26144
	ds_read_b64_tr_b16 v[142:143], v116 offset:30496
	ds_read_b64_tr_b16 v[144:145], v116 offset:17472
	ds_read_b64_tr_b16 v[146:147], v116 offset:21824
	ds_read_b64_tr_b16 v[148:149], v116 offset:26176
	ds_read_b64_tr_b16 v[150:151], v116 offset:30528
	ds_read_b64_tr_b16 v[152:153], v116 offset:17504
	ds_read_b64_tr_b16 v[154:155], v116 offset:21856
	ds_read_b64_tr_b16 v[156:157], v116 offset:26208
	ds_read_b64_tr_b16 v[158:159], v116 offset:30560
	s_cmp_lt_u32 s1, 6
	s_cbranch_scc1 .Lfb_fastscore
	s_waitcnt lgkmcnt(15)
	v_fmac_f32_e32 v124, 0x3db504f3, v196
	v_fmac_f32_e32 v120, 0x3db504f3, v197
	v_fmac_f32_e32 v125, 0x3db504f3, v198
	v_fmac_f32_e32 v122, 0x3db504f3, v199
	v_fmac_f32_e32 v123, 0x3db504f3, v200
	v_fmac_f32_e32 v126, 0x3db504f3, v201
	v_fmac_f32_e32 v97, 0x3db504f3, v202
	v_fmac_f32_e32 v98, 0x3db504f3, v203
	v_fmac_f32_e32 v99, 0x3db504f3, v204
	v_fmac_f32_e32 v92, 0x3db504f3, v205
	v_fmac_f32_e32 v121, 0x3db504f3, v206
	v_fmac_f32_e32 v94, 0x3db504f3, v207
	v_fmac_f32_e32 v95, 0x3db504f3, v208
	v_fmac_f32_e32 v127, 0x3db504f3, v209
	v_fmac_f32_e32 v93, 0x3db504f3, v210
	v_fmac_f32_e32 v119, 0x3db504f3, v211
	s_branch .Lfb_max
; __device__ __forceinline__ void attn_item(KP P, int l, bool isS, int b, int c, int hp, char* smem) {
;     ...
;       for (int j = 0; j < 4; ++j) {
;         const int jb = t * 64 + kb * 16 + fq * 4 + j;
;         const bool valid = (!isS) || (jb < 528);
;         int rel = qi + 512 - jb; rel = rel < -128 ? -128 : (rel > 128 ? 128 : rel);
;         const float v = valid ? s[kb][j] * scl + Bi[rel + 128] : -1e30f;
;         s[kb][j] = v;
;         mx = fmaxf(mx, v);
;       }
.Lfb_fastscore:
	s_waitcnt lgkmcnt(15)
	v_fma_f32 v124, v221, v196, v220
	v_fma_f32 v120, v221, v197, v220
	v_fma_f32 v125, v221, v198, v220
	v_fma_f32 v122, v221, v199, v220
	v_fma_f32 v123, v221, v200, v220
	v_fma_f32 v126, v221, v201, v220
	v_fma_f32 v97, v221, v202, v220
	v_fma_f32 v98, v221, v203, v220
	v_fma_f32 v99, v221, v204, v220
	v_fma_f32 v92, v221, v205, v220
	v_fma_f32 v121, v221, v206, v220
	v_fma_f32 v94, v221, v207, v220
	v_fma_f32 v95, v221, v208, v220
	v_fma_f32 v127, v221, v209, v220
	v_fma_f32 v93, v221, v210, v220
	v_fma_f32 v119, v221, v211, v220
; __device__ __forceinline__ bf16x8 cat44(s16x4 a, s16x4 b) { return (bf16x8){a[0], a[1], a[2], a[3], b[0], b[1], b[2], b[3]}; }
; __device__ __forceinline__ void attn_item(KP P, int l, bool isS, int b, int c, int hp, char* smem) {
;     ...
;     mx = fmaxf(mx, sx<16>(mx));
;     mx = fmaxf(mx, bperm(mx, lane ^ 32));
;     const float mn = fmaxf(mrow, mx);
;     const float alpha = __expf(mrow - mn);
;     mrow = mn;
;     lrow *= alpha;
;     bf16x8 pf[2];
; #pragma unroll
;     for (int kr = 0; kr < 2; ++kr) {
;       float p[8];
; #pragma unroll
;       for (int i = 0; i < 8; ++i) {
;         const int kb = kr * 2 + (i >> 2), j = i & 3;
;         const int jb = t * 64 + kb * 16 + fq * 4 + j;
;         const bool valid = (!isS) || (jb < 528);
;         p[i] = valid ? __expf(s[kb][j] - mn) : 0.f;
;         lrow += p[i];
;       }
;       pf[kr] = as_bf16x8(pack8(p));
;     }
; #pragma unroll
;     for (int db = 0; db < 8; ++db) {
; #pragma unroll
;       for (int j = 0; j < 4; ++j) o[db][j] *= alpha;
;     }
;     const int trr = fq * 4 + ((lane >> 2) & 3), trc = (lane & 3) * 4;
; #pragma unroll
;     for (int db = 0; db < 8; ++db) {
; #pragma unroll
;       for (int kr = 0; kr < 2; ++kr) {
;         const u16* p0 = Vs + (kr * 32 + trr) * 136 + db * 16 + trc;
;         const bf16x8 vf = cat44(ldtr(p0), ldtr(p0 + 16 * 136));
;         o[db] = __builtin_amdgcn_mfma_f32_16x16x32_bf16(vf, pf[kr], o[db], 0, 0, 0);
;       }
;     }
;     __syncthreads();
;   }
.Lfb_max:
	v_max3_f32 v88, v124, s34, v120
	v_max3_f32 v88, v88, v125, v122
	v_max3_f32 v88, v88, v123, v126
	v_max3_f32 v88, v88, v97, v98
	v_max3_f32 v88, v88, v99, v92
	v_max3_f32 v88, v88, v121, v94
	v_max3_f32 v88, v88, v95, v127
	v_max3_f32 v88, v88, v93, v119
	ds_swizzle_b32 v89, v88 offset:swizzle(SWAP,16)
	s_waitcnt lgkmcnt(0)
	v_max_f32_e32 v89, v89, v89
	v_max_f32_e32 v88, v88, v89
	ds_bpermute_b32 v89, v112, v88
	s_waitcnt lgkmcnt(0)
	ds_read_b64_tr_b16 v[160:161], v116 offset:17536
	ds_read_b64_tr_b16 v[162:163], v116 offset:21888
	ds_read_b64_tr_b16 v[164:165], v116 offset:26240
	ds_read_b64_tr_b16 v[166:167], v116 offset:30592
	ds_read_b64_tr_b16 v[168:169], v116 offset:17568
	ds_read_b64_tr_b16 v[170:171], v116 offset:21920
	ds_read_b64_tr_b16 v[172:173], v116 offset:26272
	ds_read_b64_tr_b16 v[174:175], v116 offset:30624
	ds_read_b64_tr_b16 v[176:177], v116 offset:17600
	ds_read_b64_tr_b16 v[178:179], v116 offset:21952
	ds_read_b64_tr_b16 v[180:181], v116 offset:26304
	ds_read_b64_tr_b16 v[182:183], v116 offset:30656
	ds_read_b64_tr_b16 v[184:185], v116 offset:17632
	ds_read_b64_tr_b16 v[186:187], v116 offset:21984
	ds_read_b64_tr_b16 v[192:193], v116 offset:26336
	ds_read_b64_tr_b16 v[194:195], v116 offset:30688
	v_max3_f32 v96, v118, v88, v89
	v_sub_f32_e32 v88, v118, v96
	v_mul_f32_e32 v88, 0x3fb8aa3b, v88
	v_exp_f32_e32 v118, v88
	v_sub_f32_e32 v88, v124, v96
	v_mul_f32_e32 v88, 0x3fb8aa3b, v88
	v_exp_f32_e32 v88, v88
	v_sub_f32_e32 v90, v120, v96
	v_mul_f32_e32 v90, 0x3fb8aa3b, v90
	v_sub_f32_e32 v91, v125, v96
	v_fma_f32 v89, v117, v118, v88
	v_exp_f32_e32 v90, v90
	v_mul_f32_e32 v91, 0x3fb8aa3b, v91
	v_sub_f32_e32 v117, v122, v96
	v_exp_f32_e32 v91, v91
	v_mul_f32_e32 v117, 0x3fb8aa3b, v117
	v_sub_f32_e32 v120, v123, v96
	v_exp_f32_e32 v117, v117
	v_mul_f32_e32 v120, 0x3fb8aa3b, v120
	v_sub_f32_e32 v122, v126, v96
	v_exp_f32_e32 v120, v120
	v_mul_f32_e32 v122, 0x3fb8aa3b, v122
	v_sub_f32_e32 v97, v97, v96
	v_add_f32_e32 v89, v90, v89
	v_exp_f32_e32 v122, v122
	v_mul_f32_e32 v97, 0x3fb8aa3b, v97
	v_sub_f32_e32 v98, v98, v96
	v_add_f32_e32 v89, v91, v89
	v_exp_f32_e32 v97, v97
	v_mul_f32_e32 v98, 0x3fb8aa3b, v98
	v_add_f32_e32 v89, v117, v89
	v_exp_f32_e32 v98, v98
	v_add_f32_e32 v89, v120, v89
	v_add_f32_e32 v89, v122, v89
	v_add_f32_e32 v89, v97, v89
	v_bfe_u32 v124, v122, 16, 1
	v_bfe_u32 v125, v117, 16, 1
	v_bfe_u32 v126, v90, 16, 1
	v_add_f32_e32 v123, v98, v89
	v_bfe_u32 v89, v98, 16, 1
	v_add3_u32 v126, v90, v126, s33
	v_add3_u32 v117, v117, v125, s33
	v_add3_u32 v90, v122, v124, s33
	v_bfe_u32 v122, v91, 16, 1
	v_bfe_u32 v125, v97, 16, 1
	v_add3_u32 v89, v98, v89, s33
	v_bfe_u32 v98, v88, 16, 1
	v_add3_u32 v97, v97, v125, s33
	v_add3_u32 v91, v91, v122, s33
	v_add3_u32 v88, v88, v98, s33
	v_lshrrev_b32_e32 v98, 16, v91
	v_lshrrev_b32_e32 v91, 16, v97
	v_sub_f32_e32 v97, v99, v96
	v_mul_f32_e32 v97, 0x3fb8aa3b, v97
	v_sub_f32_e32 v92, v92, v96
	v_and_or_b32 v91, v89, s30, v91
	v_and_or_b32 v89, v117, s30, v98
	v_exp_f32_e32 v99, v97
	v_mul_f32_e32 v92, 0x3fb8aa3b, v92
	v_sub_f32_e32 v98, v121, v96
	v_bfe_u32 v124, v120, 16, 1
	v_exp_f32_e32 v92, v92
	v_mul_f32_e32 v98, 0x3fb8aa3b, v98
	v_sub_f32_e32 v94, v94, v96
	v_add3_u32 v120, v120, v124, s33
	v_exp_f32_e32 v117, v98
	v_mul_f32_e32 v94, 0x3fb8aa3b, v94
	v_sub_f32_e32 v95, v95, v96
	v_sub_f32_e32 v98, v127, v96
	v_lshrrev_b32_e32 v120, 16, v120
	v_exp_f32_e32 v94, v94
	v_mul_f32_e32 v95, 0x3fb8aa3b, v95
	v_mul_f32_e32 v98, 0x3fb8aa3b, v98
	v_sub_f32_e32 v93, v93, v96
	v_and_or_b32 v90, v90, s30, v120
	v_add_f32_e32 v97, v99, v123
	v_exp_f32_e32 v95, v95
	v_exp_f32_e32 v120, v98
	v_mul_f32_e32 v93, 0x3fb8aa3b, v93
	v_sub_f32_e32 v98, v119, v96
	v_add_f32_e32 v97, v92, v97
	v_exp_f32_e32 v93, v93
	v_mul_f32_e32 v98, 0x3fb8aa3b, v98
	v_add_f32_e32 v97, v117, v97
	v_exp_f32_e32 v98, v98
	v_add_f32_e32 v97, v94, v97
	v_add_f32_e32 v97, v95, v97
	v_bfe_u32 v121, v120, 16, 1
	v_bfe_u32 v122, v94, 16, 1
	v_bfe_u32 v123, v92, 16, 1
	v_add_f32_e32 v97, v120, v97
	v_add3_u32 v92, v92, v123, s33
	v_add3_u32 v122, v94, v122, s33
	v_add3_u32 v94, v120, v121, s33
	v_bfe_u32 v121, v117, 16, 1
	v_bfe_u32 v123, v95, 16, 1
	v_bfe_u32 v124, v93, 16, 1
	v_add_f32_e32 v97, v93, v97
	v_bfe_u32 v119, v98, 16, 1
	v_bfe_u32 v120, v99, 16, 1
	v_add3_u32 v93, v93, v124, s33
	v_add3_u32 v95, v95, v123, s33
	v_add3_u32 v117, v117, v121, s33
	v_add3_u32 v119, v98, v119, s33
	v_add3_u32 v99, v99, v120, s33
	v_lshrrev_b32_e32 v117, 16, v117
	v_lshrrev_b32_e32 v120, 16, v95
	v_lshrrev_b32_e32 v93, 16, v93
	v_and_or_b32 v95, v119, s30, v93
	v_and_or_b32 v94, v94, s30, v120
	v_and_or_b32 v93, v122, s30, v117
	v_pk_mul_f32 v[58:59], v[58:59], v[118:119] op_sel_hi:[1,0]
	v_pk_mul_f32 v[56:57], v[56:57], v[118:119] op_sel_hi:[1,0]
	v_pk_mul_f32 v[46:47], v[46:47], v[118:119] op_sel_hi:[1,0]
	v_pk_mul_f32 v[44:45], v[44:45], v[118:119] op_sel_hi:[1,0]
	v_pk_mul_f32 v[54:55], v[54:55], v[118:119] op_sel_hi:[1,0]
	v_pk_mul_f32 v[52:53], v[52:53], v[118:119] op_sel_hi:[1,0]
	v_pk_mul_f32 v[74:75], v[74:75], v[118:119] op_sel_hi:[1,0]
	v_pk_mul_f32 v[72:73], v[72:73], v[118:119] op_sel_hi:[1,0]
	v_pk_mul_f32 v[78:79], v[78:79], v[118:119] op_sel_hi:[1,0]
	v_pk_mul_f32 v[76:77], v[76:77], v[118:119] op_sel_hi:[1,0]
	v_pk_mul_f32 v[70:71], v[70:71], v[118:119] op_sel_hi:[1,0]
	v_pk_mul_f32 v[68:69], v[68:69], v[118:119] op_sel_hi:[1,0]
	v_pk_mul_f32 v[82:83], v[82:83], v[118:119] op_sel_hi:[1,0]
	v_pk_mul_f32 v[80:81], v[80:81], v[118:119] op_sel_hi:[1,0]
	v_pk_mul_f32 v[86:87], v[86:87], v[118:119] op_sel_hi:[1,0]
	v_pk_mul_f32 v[84:85], v[84:85], v[118:119] op_sel_hi:[1,0]
	v_lshrrev_b32_e32 v88, 16, v88
	v_and_or_b32 v88, v126, s30, v88
	v_lshrrev_b32_e32 v99, 16, v99
	v_and_or_b32 v92, v92, s30, v99
	v_add_f32_e32 v117, v98, v97
	s_waitcnt lgkmcnt(0)
	s_barrier
	v_mfma_f32_16x16x32_bf16 v[56:59], v[128:131], v[88:91], v[56:59]
	v_mfma_f32_16x16x32_bf16 v[56:59], v[132:135], v[92:95], v[56:59]
	v_mfma_f32_16x16x32_bf16 v[44:47], v[136:139], v[88:91], v[44:47]
	v_mfma_f32_16x16x32_bf16 v[44:47], v[140:143], v[92:95], v[44:47]
	v_mfma_f32_16x16x32_bf16 v[52:55], v[144:147], v[88:91], v[52:55]
	v_mfma_f32_16x16x32_bf16 v[52:55], v[148:151], v[92:95], v[52:55]
	v_mfma_f32_16x16x32_bf16 v[72:75], v[152:155], v[88:91], v[72:75]
	v_mfma_f32_16x16x32_bf16 v[72:75], v[156:159], v[92:95], v[72:75]
	v_mfma_f32_16x16x32_bf16 v[76:79], v[160:163], v[88:91], v[76:79]
	v_mfma_f32_16x16x32_bf16 v[76:79], v[164:167], v[92:95], v[76:79]
	v_mfma_f32_16x16x32_bf16 v[68:71], v[168:171], v[88:91], v[68:71]
	v_mfma_f32_16x16x32_bf16 v[68:71], v[172:175], v[92:95], v[68:71]
	v_mfma_f32_16x16x32_bf16 v[80:83], v[176:179], v[88:91], v[80:83]
	v_mfma_f32_16x16x32_bf16 v[80:83], v[180:183], v[92:95], v[80:83]
	v_mfma_f32_16x16x32_bf16 v[84:87], v[184:187], v[88:91], v[84:87]
	v_mfma_f32_16x16x32_bf16 v[84:87], v[192:195], v[92:95], v[84:87]
	s_cmp_gt_u32 s1, 7
	s_cbranch_scc1 .LBB0_472
	v_mov_b32_e32 v118, v96
	s_branch .LBB0_476
